# row-wise phases P3 and P11 software-pipelined: next row's loads issued before the current row's math (2 register sets), loop-invariant gamma loads hoisted
# baseline (speedup 1.0000x reference)
.LBB0_173:
	global_load_dwordx4 v[212:215], v[34:35], off
	global_load_dwordx4 v[208:211], v[34:35], off offset:1024
	global_load_dwordx4 v[204:207], v[34:35], off offset:2048
	global_load_dwordx4 v[200:203], v[34:35], off offset:3072
	global_load_dwordx4 v[58:61], v[36:37], off
	global_load_dwordx4 v[62:65], v[36:37], off offset:1024
	global_load_dwordx4 v[66:69], v[36:37], off offset:2048
	global_load_dwordx4 v[70:73], v[36:37], off offset:3072
	global_load_dwordx2 v[42:43], v[38:39], off offset:-1536
	global_load_dwordx2 v[44:45], v[38:39], off offset:-1024
	global_load_dwordx2 v[46:47], v[38:39], off offset:-512
	global_load_dwordx2 v[48:49], v[38:39], off
	global_load_dwordx4 v[14:17], v[40:41], off offset:-2048
	global_load_dwordx4 v[10:13], v[40:41], off offset:-1024
	global_load_dwordx4 v[6:9], v[40:41], off
	global_load_dwordx4 v[2:5], v[40:41], off offset:1024
	v_add_co_u32_e32 v74, vcc, s7, v38
	s_add_i32 s4, s4, s6
	s_nop 0
	v_addc_co_u32_e32 v75, vcc, -1, v39, vcc
	v_lshl_add_u64 v[38:39], v[38:39], 0, s[8:9]
	v_lshl_add_u64 v[40:41], v[40:41], 0, s[12:13]
	s_cmp_lt_i32 s4, 0x8000
	s_cbranch_scc0 .Lp3_tailA
	global_load_dwordx2 v[142:143], v[38:39], off offset:-1536
	global_load_dwordx2 v[144:145], v[38:39], off offset:-1024
	global_load_dwordx2 v[146:147], v[38:39], off offset:-512
	global_load_dwordx2 v[148:149], v[38:39], off
	global_load_dwordx4 v[114:117], v[40:41], off offset:-2048
	global_load_dwordx4 v[110:113], v[40:41], off offset:-1024
	global_load_dwordx4 v[106:109], v[40:41], off
	global_load_dwordx4 v[102:105], v[40:41], off offset:1024
	s_waitcnt vmcnt(8)
	s_branch .Lp3_compA
.Lp3_loop:
	v_add_co_u32_e32 v74, vcc, s7, v38
	s_add_i32 s4, s4, s6
	s_nop 0
	v_addc_co_u32_e32 v75, vcc, -1, v39, vcc
	v_lshl_add_u64 v[38:39], v[38:39], 0, s[8:9]
	v_lshl_add_u64 v[40:41], v[40:41], 0, s[12:13]
	s_cmp_lt_i32 s4, 0x8000
	s_cbranch_scc0 .Lp3_tailA
	global_load_dwordx2 v[142:143], v[38:39], off offset:-1536
	global_load_dwordx2 v[144:145], v[38:39], off offset:-1024
	global_load_dwordx2 v[146:147], v[38:39], off offset:-512
	global_load_dwordx2 v[148:149], v[38:39], off
	global_load_dwordx4 v[114:117], v[40:41], off offset:-2048
	global_load_dwordx4 v[110:113], v[40:41], off offset:-1024
	global_load_dwordx4 v[106:109], v[40:41], off
	global_load_dwordx4 v[102:105], v[40:41], off offset:1024
	s_waitcnt vmcnt(12)
.Lp3_compA:
	v_lshlrev_b32_e32 v76, 16, v42
	v_and_b32_e32 v77, 0xffff0000, v42
	v_lshlrev_b32_e32 v42, 16, v43
	v_and_b32_e32 v43, 0xffff0000, v43
	v_lshlrev_b32_e32 v78, 16, v44
	v_and_b32_e32 v79, 0xffff0000, v44
	v_lshlrev_b32_e32 v44, 16, v45
	v_and_b32_e32 v45, 0xffff0000, v45
	v_lshlrev_b32_e32 v80, 16, v46
	v_and_b32_e32 v81, 0xffff0000, v46
	v_lshlrev_b32_e32 v46, 16, v47
	v_and_b32_e32 v47, 0xffff0000, v47
	v_mul_f32_e32 v57, v77, v77
	v_mul_f32_e32 v84, v43, v43
	v_mul_f32_e32 v85, v79, v79
	v_mul_f32_e32 v86, v45, v45
	v_lshlrev_b32_e32 v82, 16, v48
	v_and_b32_e32 v83, 0xffff0000, v48
	v_lshlrev_b32_e32 v48, 16, v49
	v_and_b32_e32 v49, 0xffff0000, v49
	v_mul_f32_e32 v87, v81, v81
	v_mul_f32_e32 v88, v47, v47
	v_fmac_f32_e32 v57, v76, v76
	v_fmac_f32_e32 v84, v42, v42
	v_fmac_f32_e32 v85, v78, v78
	v_fmac_f32_e32 v86, v44, v44
	v_mul_f32_e32 v89, v83, v83
	v_mul_f32_e32 v90, v49, v49
	v_fmac_f32_e32 v87, v80, v80
	v_fmac_f32_e32 v88, v46, v46
	v_add_f32_e32 v57, v57, v84
	v_add_f32_e32 v84, v85, v86
	v_fmac_f32_e32 v89, v82, v82
	v_fmac_f32_e32 v90, v48, v48
	v_add_f32_e32 v85, v87, v88
	v_add_f32_e32 v57, v57, v84
	v_add_f32_e32 v86, v89, v90
	v_add_f32_e32 v57, v57, v85
	v_add_f32_e32 v57, v57, v86
	ds_bpermute_b32 v84, v1, v57
	s_waitcnt lgkmcnt(0)
	v_add_f32_e32 v57, v57, v84
	ds_bpermute_b32 v84, v50, v57
	s_waitcnt lgkmcnt(0)
	v_add_f32_e32 v57, v57, v84
	ds_bpermute_b32 v84, v51, v57
	s_waitcnt lgkmcnt(0)
	v_add_f32_e32 v57, v57, v84
	ds_bpermute_b32 v84, v52, v57
	s_waitcnt lgkmcnt(0)
	v_add_f32_e32 v57, v57, v84
	ds_bpermute_b32 v84, v53, v57
	s_waitcnt lgkmcnt(0)
	v_add_f32_e32 v57, v57, v84
	ds_bpermute_b32 v84, v54, v57
	s_waitcnt lgkmcnt(0)
	v_add_f32_e32 v57, v57, v84
	v_fmamk_f32 v57, v57, 0x3a800000, v55
	v_mul_f32_e32 v84, 0x4f800000, v57
	v_cmp_gt_f32_e32 vcc, s5, v57
	s_nop 1
	v_cndmask_b32_e32 v57, v57, v84, vcc
	v_sqrt_f32_e32 v84, v57
	s_nop 0
	v_add_u32_e32 v85, -1, v84
	v_add_u32_e32 v86, 1, v84
	v_fma_f32 v87, -v85, v84, v57
	v_fma_f32 v88, -v86, v84, v57
	v_cmp_ge_f32_e64 s[2:3], 0, v87
	s_nop 1
	v_cndmask_b32_e64 v84, v84, v85, s[2:3]
	v_cmp_lt_f32_e64 s[2:3], 0, v88
	s_nop 1
	v_cndmask_b32_e64 v84, v84, v86, s[2:3]
	v_mul_f32_e32 v85, 0x37800000, v84
	v_cndmask_b32_e32 v84, v84, v85, vcc
	v_cmp_class_f32_e32 vcc, v57, v56
	s_nop 1
	v_cndmask_b32_e32 v57, v84, v57, vcc
	v_div_scale_f32 v84, s[2:3], v57, v57, 1.0
	v_rcp_f32_e32 v86, v84
	v_div_scale_f32 v85, vcc, 1.0, v57, 1.0
	v_fma_f32 v87, -v84, v86, 1.0
	v_fmac_f32_e32 v86, v87, v86
	v_mul_f32_e32 v87, v85, v86
	v_fma_f32 v88, -v84, v87, v85
	v_fmac_f32_e32 v87, v88, v86
	v_fma_f32 v84, -v84, v87, v85
	v_div_fmas_f32 v84, v84, v86, v87
	v_div_fixup_f32 v57, v84, v57, 1.0
	v_mul_f32_e32 v84, 0.5, v57
	v_pk_mul_f32 v[42:43], v[84:85], v[42:43] op_sel_hi:[0,1]
	v_pk_mul_f32 v[76:77], v[84:85], v[76:77] op_sel_hi:[0,1]
	v_pk_mul_f32 v[44:45], v[84:85], v[44:45] op_sel_hi:[0,1]
	v_pk_mul_f32 v[78:79], v[84:85], v[78:79] op_sel_hi:[0,1]
	v_pk_mul_f32 v[80:81], v[84:85], v[80:81] op_sel_hi:[0,1]
	v_pk_mul_f32 v[46:47], v[84:85], v[46:47] op_sel_hi:[0,1]
	v_pk_mul_f32 v[82:83], v[84:85], v[82:83] op_sel_hi:[0,1]
	v_pk_mul_f32 v[48:49], v[84:85], v[48:49] op_sel_hi:[0,1]
	v_pk_fma_f32 v[14:15], v[212:213], v[76:77], v[14:15]
	v_pk_fma_f32 v[16:17], v[214:215], v[42:43], v[16:17]
	v_pk_fma_f32 v[10:11], v[208:209], v[78:79], v[10:11]
	v_pk_fma_f32 v[12:13], v[210:211], v[44:45], v[12:13]
	v_pk_fma_f32 v[8:9], v[206:207], v[46:47], v[8:9]
	v_pk_fma_f32 v[6:7], v[204:205], v[80:81], v[6:7]
	v_pk_fma_f32 v[4:5], v[202:203], v[48:49], v[4:5]
	v_pk_fma_f32 v[2:3], v[200:201], v[82:83], v[2:3]
	v_pk_mul_f32 v[18:19], v[16:17], v[16:17]
	v_pk_mul_f32 v[20:21], v[14:15], v[14:15]
	v_pk_mul_f32 v[22:23], v[12:13], v[12:13]
	v_pk_mul_f32 v[24:25], v[10:11], v[10:11]
	v_pk_mov_b32 v[30:31], v[20:21], v[18:19] op_sel:[1,0]
	v_mov_b32_e32 v21, v19
	v_pk_mov_b32 v[18:19], v[24:25], v[22:23] op_sel:[1,0]
	v_mov_b32_e32 v25, v23
	v_mul_f32_e32 v26, v6, v6
	v_mul_f32_e32 v28, v8, v8
	v_pk_add_f32 v[20:21], v[30:31], v[20:21]
	v_pk_add_f32 v[18:19], v[18:19], v[24:25]
	v_pk_fma_f32 v[22:23], v[6:7], v[6:7], v[26:27] op_sel_hi:[1,1,0]
	v_pk_fma_f32 v[26:27], v[8:9], v[8:9], v[28:29] op_sel_hi:[1,1,0]
	v_pk_add_f32 v[20:21], v[20:21], v[20:21] op_sel_hi:[0,1]
	v_pk_add_f32 v[18:19], v[18:19], v[18:19] op_sel_hi:[0,1]
	v_mul_f32_e32 v22, v2, v2
	v_mul_f32_e32 v26, v3, v3
	v_mul_f32_e32 v20, v4, v4
	v_mul_f32_e32 v18, v5, v5
	v_pk_add_f32 v[22:23], v[22:23], v[26:27]
	v_pk_add_f32 v[18:19], v[20:21], v[18:19]
	s_nop 0
	v_pk_add_f32 v[18:19], v[22:23], v[18:19]
	s_nop 0
	v_add_f32_e32 v18, v18, v19
	ds_bpermute_b32 v19, v1, v18
	s_waitcnt lgkmcnt(0)
	v_add_f32_e32 v18, v18, v19
	ds_bpermute_b32 v19, v50, v18
	s_waitcnt lgkmcnt(0)
	v_add_f32_e32 v18, v18, v19
	ds_bpermute_b32 v19, v51, v18
	s_waitcnt lgkmcnt(0)
	v_add_f32_e32 v18, v18, v19
	ds_bpermute_b32 v19, v52, v18
	s_waitcnt lgkmcnt(0)
	v_add_f32_e32 v18, v18, v19
	ds_bpermute_b32 v19, v53, v18
	s_waitcnt lgkmcnt(0)
	v_add_f32_e32 v18, v18, v19
	ds_bpermute_b32 v19, v54, v18
	s_waitcnt lgkmcnt(0)
	v_add_f32_e32 v18, v18, v19
	v_fmamk_f32 v18, v18, 0x3a800000, v55
	v_mul_f32_e32 v19, 0x4f800000, v18
	v_cmp_gt_f32_e32 vcc, s5, v18
	s_nop 1
	v_cndmask_b32_e32 v18, v18, v19, vcc
	v_sqrt_f32_e32 v19, v18
	s_nop 0
	v_add_u32_e32 v20, -1, v19
	v_add_u32_e32 v21, 1, v19
	v_fma_f32 v22, -v20, v19, v18
	v_fma_f32 v23, -v21, v19, v18
	v_cmp_ge_f32_e64 s[2:3], 0, v22
	s_nop 1
	v_cndmask_b32_e64 v19, v19, v20, s[2:3]
	v_cmp_lt_f32_e64 s[2:3], 0, v23
	s_nop 1
	v_cndmask_b32_e64 v19, v19, v21, s[2:3]
	v_mul_f32_e32 v20, 0x37800000, v19
	v_cndmask_b32_e32 v19, v19, v20, vcc
	v_cmp_class_f32_e32 vcc, v18, v56
	s_nop 1
	v_cndmask_b32_e32 v18, v19, v18, vcc
	v_div_scale_f32 v19, s[2:3], v18, v18, 1.0
	v_rcp_f32_e32 v21, v19
	v_div_scale_f32 v20, vcc, 1.0, v18, 1.0
	v_fma_f32 v22, -v19, v21, 1.0
	v_fmac_f32_e32 v21, v22, v21
	v_mul_f32_e32 v22, v20, v21
	v_fma_f32 v23, -v19, v22, v20
	v_fmac_f32_e32 v22, v23, v21
	v_fma_f32 v19, -v19, v22, v20
	v_div_fmas_f32 v19, v19, v21, v22
	v_div_fixup_f32 v18, v19, v18, 1.0
	v_pk_mul_f32 v[14:15], v[14:15], v[18:19] op_sel_hi:[1,0]
	v_pk_mul_f32 v[16:17], v[16:17], v[18:19] op_sel_hi:[1,0]
	v_pk_mul_f32 v[10:11], v[10:11], v[18:19] op_sel_hi:[1,0]
	v_pk_mul_f32 v[12:13], v[12:13], v[18:19] op_sel_hi:[1,0]
	v_pk_mul_f32 v[6:7], v[6:7], v[18:19] op_sel_hi:[1,0]
	v_pk_mul_f32 v[8:9], v[8:9], v[18:19] op_sel_hi:[1,0]
	v_pk_mul_f32 v[2:3], v[2:3], v[18:19] op_sel_hi:[1,0]
	v_pk_mul_f32 v[4:5], v[4:5], v[18:19] op_sel_hi:[1,0]
	v_pk_mul_f32 v[16:17], v[60:61], v[16:17]
	v_pk_mul_f32 v[14:15], v[58:59], v[14:15]
	v_pk_mul_f32 v[12:13], v[64:65], v[12:13]
	v_pk_mul_f32 v[10:11], v[62:63], v[10:11]
	v_pk_mul_f32 v[8:9], v[68:69], v[8:9]
	v_pk_mul_f32 v[6:7], v[66:67], v[6:7]
	v_pk_mul_f32 v[4:5], v[72:73], v[4:5]
	v_pk_mul_f32 v[2:3], v[70:71], v[2:3]
	v_cvt_pk_bf16_f32 v14, v14, v15
	v_cvt_pk_bf16_f32 v15, v16, v17
	v_cvt_pk_bf16_f32 v10, v10, v11
	v_cvt_pk_bf16_f32 v11, v12, v13
	v_cvt_pk_bf16_f32 v6, v6, v7
	v_cvt_pk_bf16_f32 v7, v8, v9
	v_cvt_pk_bf16_f32 v2, v2, v3
	v_cvt_pk_bf16_f32 v3, v4, v5
	global_store_dwordx2 v[74:75], v[14:15], off offset:-1536
	global_store_dwordx2 v[74:75], v[10:11], off offset:-1024
	global_store_dwordx2 v[74:75], v[6:7], off offset:-512
	global_store_dwordx2 v[74:75], v[2:3], off
	v_add_co_u32_e32 v174, vcc, s7, v38
	s_add_i32 s4, s4, s6
	s_nop 0
	v_addc_co_u32_e32 v175, vcc, -1, v39, vcc
	v_lshl_add_u64 v[38:39], v[38:39], 0, s[8:9]
	v_lshl_add_u64 v[40:41], v[40:41], 0, s[12:13]
	s_cmp_lt_i32 s4, 0x8000
	s_cbranch_scc0 .Lp3_tailB
	global_load_dwordx2 v[42:43], v[38:39], off offset:-1536
	global_load_dwordx2 v[44:45], v[38:39], off offset:-1024
	global_load_dwordx2 v[46:47], v[38:39], off offset:-512
	global_load_dwordx2 v[48:49], v[38:39], off
	global_load_dwordx4 v[14:17], v[40:41], off offset:-2048
	global_load_dwordx4 v[10:13], v[40:41], off offset:-1024
	global_load_dwordx4 v[6:9], v[40:41], off
	global_load_dwordx4 v[2:5], v[40:41], off offset:1024
	s_waitcnt vmcnt(12)
	v_lshlrev_b32_e32 v176, 16, v142
	v_and_b32_e32 v177, 0xffff0000, v142
	v_lshlrev_b32_e32 v142, 16, v143
	v_and_b32_e32 v143, 0xffff0000, v143
	v_lshlrev_b32_e32 v178, 16, v144
	v_and_b32_e32 v179, 0xffff0000, v144
	v_lshlrev_b32_e32 v144, 16, v145
	v_and_b32_e32 v145, 0xffff0000, v145
	v_lshlrev_b32_e32 v180, 16, v146
	v_and_b32_e32 v181, 0xffff0000, v146
	v_lshlrev_b32_e32 v146, 16, v147
	v_and_b32_e32 v147, 0xffff0000, v147
	v_mul_f32_e32 v157, v177, v177
	v_mul_f32_e32 v184, v143, v143
	v_mul_f32_e32 v185, v179, v179
	v_mul_f32_e32 v186, v145, v145
	v_lshlrev_b32_e32 v182, 16, v148
	v_and_b32_e32 v183, 0xffff0000, v148
	v_lshlrev_b32_e32 v148, 16, v149
	v_and_b32_e32 v149, 0xffff0000, v149
	v_mul_f32_e32 v187, v181, v181
	v_mul_f32_e32 v188, v147, v147
	v_fmac_f32_e32 v157, v176, v176
	v_fmac_f32_e32 v184, v142, v142
	v_fmac_f32_e32 v185, v178, v178
	v_fmac_f32_e32 v186, v144, v144
	v_mul_f32_e32 v189, v183, v183
	v_mul_f32_e32 v190, v149, v149
	v_fmac_f32_e32 v187, v180, v180
	v_fmac_f32_e32 v188, v146, v146
	v_add_f32_e32 v157, v157, v184
	v_add_f32_e32 v184, v185, v186
	v_fmac_f32_e32 v189, v182, v182
	v_fmac_f32_e32 v190, v148, v148
	v_add_f32_e32 v185, v187, v188
	v_add_f32_e32 v157, v157, v184
	v_add_f32_e32 v186, v189, v190
	v_add_f32_e32 v157, v157, v185
	v_add_f32_e32 v157, v157, v186
	ds_bpermute_b32 v184, v1, v157
	s_waitcnt lgkmcnt(0)
	v_add_f32_e32 v157, v157, v184
	ds_bpermute_b32 v184, v50, v157
	s_waitcnt lgkmcnt(0)
	v_add_f32_e32 v157, v157, v184
	ds_bpermute_b32 v184, v51, v157
	s_waitcnt lgkmcnt(0)
	v_add_f32_e32 v157, v157, v184
	ds_bpermute_b32 v184, v52, v157
	s_waitcnt lgkmcnt(0)
	v_add_f32_e32 v157, v157, v184
	ds_bpermute_b32 v184, v53, v157
	s_waitcnt lgkmcnt(0)
	v_add_f32_e32 v157, v157, v184
	ds_bpermute_b32 v184, v54, v157
	s_waitcnt lgkmcnt(0)
	v_add_f32_e32 v157, v157, v184
	v_fmamk_f32 v157, v157, 0x3a800000, v55
	v_mul_f32_e32 v184, 0x4f800000, v157
	v_cmp_gt_f32_e32 vcc, s5, v157
	s_nop 1
	v_cndmask_b32_e32 v157, v157, v184, vcc
	v_sqrt_f32_e32 v184, v157
	s_nop 0
	v_add_u32_e32 v185, -1, v184
	v_add_u32_e32 v186, 1, v184
	v_fma_f32 v187, -v185, v184, v157
	v_fma_f32 v188, -v186, v184, v157
	v_cmp_ge_f32_e64 s[2:3], 0, v187
	s_nop 1
	v_cndmask_b32_e64 v184, v184, v185, s[2:3]
	v_cmp_lt_f32_e64 s[2:3], 0, v188
	s_nop 1
	v_cndmask_b32_e64 v184, v184, v186, s[2:3]
	v_mul_f32_e32 v185, 0x37800000, v184
	v_cndmask_b32_e32 v184, v184, v185, vcc
	v_cmp_class_f32_e32 vcc, v157, v56
	s_nop 1
	v_cndmask_b32_e32 v157, v184, v157, vcc
	v_div_scale_f32 v184, s[2:3], v157, v157, 1.0
	v_rcp_f32_e32 v186, v184
	v_div_scale_f32 v185, vcc, 1.0, v157, 1.0
	v_fma_f32 v187, -v184, v186, 1.0
	v_fmac_f32_e32 v186, v187, v186
	v_mul_f32_e32 v187, v185, v186
	v_fma_f32 v188, -v184, v187, v185
	v_fmac_f32_e32 v187, v188, v186
	v_fma_f32 v184, -v184, v187, v185
	v_div_fmas_f32 v184, v184, v186, v187
	v_div_fixup_f32 v157, v184, v157, 1.0
	v_mul_f32_e32 v184, 0.5, v157
	v_pk_mul_f32 v[142:143], v[184:185], v[142:143] op_sel_hi:[0,1]
	v_pk_mul_f32 v[176:177], v[184:185], v[176:177] op_sel_hi:[0,1]
	v_pk_mul_f32 v[144:145], v[184:185], v[144:145] op_sel_hi:[0,1]
	v_pk_mul_f32 v[178:179], v[184:185], v[178:179] op_sel_hi:[0,1]
	v_pk_mul_f32 v[180:181], v[184:185], v[180:181] op_sel_hi:[0,1]
	v_pk_mul_f32 v[146:147], v[184:185], v[146:147] op_sel_hi:[0,1]
	v_pk_mul_f32 v[182:183], v[184:185], v[182:183] op_sel_hi:[0,1]
	v_pk_mul_f32 v[148:149], v[184:185], v[148:149] op_sel_hi:[0,1]
	v_pk_fma_f32 v[114:115], v[212:213], v[176:177], v[114:115]
	v_pk_fma_f32 v[116:117], v[214:215], v[142:143], v[116:117]
	v_pk_fma_f32 v[110:111], v[208:209], v[178:179], v[110:111]
	v_pk_fma_f32 v[112:113], v[210:211], v[144:145], v[112:113]
	v_pk_fma_f32 v[108:109], v[206:207], v[146:147], v[108:109]
	v_pk_fma_f32 v[106:107], v[204:205], v[180:181], v[106:107]
	v_pk_fma_f32 v[104:105], v[202:203], v[148:149], v[104:105]
	v_pk_fma_f32 v[102:103], v[200:201], v[182:183], v[102:103]
	v_pk_mul_f32 v[118:119], v[116:117], v[116:117]
	v_pk_mul_f32 v[120:121], v[114:115], v[114:115]
	v_pk_mul_f32 v[122:123], v[112:113], v[112:113]
	v_pk_mul_f32 v[124:125], v[110:111], v[110:111]
	v_pk_mov_b32 v[130:131], v[120:121], v[118:119] op_sel:[1,0]
	v_mov_b32_e32 v121, v119
	v_pk_mov_b32 v[118:119], v[124:125], v[122:123] op_sel:[1,0]
	v_mov_b32_e32 v125, v123
	v_mul_f32_e32 v126, v106, v106
	v_mul_f32_e32 v128, v108, v108
	v_pk_add_f32 v[120:121], v[130:131], v[120:121]
	v_pk_add_f32 v[118:119], v[118:119], v[124:125]
	v_pk_fma_f32 v[122:123], v[106:107], v[106:107], v[126:127] op_sel_hi:[1,1,0]
	v_pk_fma_f32 v[126:127], v[108:109], v[108:109], v[128:129] op_sel_hi:[1,1,0]
	v_pk_add_f32 v[120:121], v[120:121], v[120:121] op_sel_hi:[0,1]
	v_pk_add_f32 v[118:119], v[118:119], v[118:119] op_sel_hi:[0,1]
	v_mul_f32_e32 v122, v102, v102
	v_mul_f32_e32 v126, v103, v103
	v_mul_f32_e32 v120, v104, v104
	v_mul_f32_e32 v118, v105, v105
	v_pk_add_f32 v[122:123], v[122:123], v[126:127]
	v_pk_add_f32 v[118:119], v[120:121], v[118:119]
	s_nop 0
	v_pk_add_f32 v[118:119], v[122:123], v[118:119]
	s_nop 0
	v_add_f32_e32 v118, v118, v119
	ds_bpermute_b32 v119, v1, v118
	s_waitcnt lgkmcnt(0)
	v_add_f32_e32 v118, v118, v119
	ds_bpermute_b32 v119, v50, v118
	s_waitcnt lgkmcnt(0)
	v_add_f32_e32 v118, v118, v119
	ds_bpermute_b32 v119, v51, v118
	s_waitcnt lgkmcnt(0)
	v_add_f32_e32 v118, v118, v119
	ds_bpermute_b32 v119, v52, v118
	s_waitcnt lgkmcnt(0)
	v_add_f32_e32 v118, v118, v119
	ds_bpermute_b32 v119, v53, v118
	s_waitcnt lgkmcnt(0)
	v_add_f32_e32 v118, v118, v119
	ds_bpermute_b32 v119, v54, v118
	s_waitcnt lgkmcnt(0)
	v_add_f32_e32 v118, v118, v119
	v_fmamk_f32 v118, v118, 0x3a800000, v55
	v_mul_f32_e32 v119, 0x4f800000, v118
	v_cmp_gt_f32_e32 vcc, s5, v118
	s_nop 1
	v_cndmask_b32_e32 v118, v118, v119, vcc
	v_sqrt_f32_e32 v119, v118
	s_nop 0
	v_add_u32_e32 v120, -1, v119
	v_add_u32_e32 v121, 1, v119
	v_fma_f32 v122, -v120, v119, v118
	v_fma_f32 v123, -v121, v119, v118
	v_cmp_ge_f32_e64 s[2:3], 0, v122
	s_nop 1
	v_cndmask_b32_e64 v119, v119, v120, s[2:3]
	v_cmp_lt_f32_e64 s[2:3], 0, v123
	s_nop 1
	v_cndmask_b32_e64 v119, v119, v121, s[2:3]
	v_mul_f32_e32 v120, 0x37800000, v119
	v_cndmask_b32_e32 v119, v119, v120, vcc
	v_cmp_class_f32_e32 vcc, v118, v56
	s_nop 1
	v_cndmask_b32_e32 v118, v119, v118, vcc
	v_div_scale_f32 v119, s[2:3], v118, v118, 1.0
	v_rcp_f32_e32 v121, v119
	v_div_scale_f32 v120, vcc, 1.0, v118, 1.0
	v_fma_f32 v122, -v119, v121, 1.0
	v_fmac_f32_e32 v121, v122, v121
	v_mul_f32_e32 v122, v120, v121
	v_fma_f32 v123, -v119, v122, v120
	v_fmac_f32_e32 v122, v123, v121
	v_fma_f32 v119, -v119, v122, v120
	v_div_fmas_f32 v119, v119, v121, v122
	v_div_fixup_f32 v118, v119, v118, 1.0
	v_pk_mul_f32 v[114:115], v[114:115], v[118:119] op_sel_hi:[1,0]
	v_pk_mul_f32 v[116:117], v[116:117], v[118:119] op_sel_hi:[1,0]
	v_pk_mul_f32 v[110:111], v[110:111], v[118:119] op_sel_hi:[1,0]
	v_pk_mul_f32 v[112:113], v[112:113], v[118:119] op_sel_hi:[1,0]
	v_pk_mul_f32 v[106:107], v[106:107], v[118:119] op_sel_hi:[1,0]
	v_pk_mul_f32 v[108:109], v[108:109], v[118:119] op_sel_hi:[1,0]
	v_pk_mul_f32 v[102:103], v[102:103], v[118:119] op_sel_hi:[1,0]
	v_pk_mul_f32 v[104:105], v[104:105], v[118:119] op_sel_hi:[1,0]
	v_pk_mul_f32 v[116:117], v[60:61], v[116:117]
	v_pk_mul_f32 v[114:115], v[58:59], v[114:115]
	v_pk_mul_f32 v[112:113], v[64:65], v[112:113]
	v_pk_mul_f32 v[110:111], v[62:63], v[110:111]
	v_pk_mul_f32 v[108:109], v[68:69], v[108:109]
	v_pk_mul_f32 v[106:107], v[66:67], v[106:107]
	v_pk_mul_f32 v[104:105], v[72:73], v[104:105]
	v_pk_mul_f32 v[102:103], v[70:71], v[102:103]
	v_cvt_pk_bf16_f32 v114, v114, v115
	v_cvt_pk_bf16_f32 v115, v116, v117
	v_cvt_pk_bf16_f32 v110, v110, v111
	v_cvt_pk_bf16_f32 v111, v112, v113
	v_cvt_pk_bf16_f32 v106, v106, v107
	v_cvt_pk_bf16_f32 v107, v108, v109
	v_cvt_pk_bf16_f32 v102, v102, v103
	v_cvt_pk_bf16_f32 v103, v104, v105
	global_store_dwordx2 v[174:175], v[114:115], off offset:-1536
	global_store_dwordx2 v[174:175], v[110:111], off offset:-1024
	global_store_dwordx2 v[174:175], v[106:107], off offset:-512
	global_store_dwordx2 v[174:175], v[102:103], off
	s_branch .Lp3_loop
.Lp3_tailA:
	s_waitcnt vmcnt(0)
	v_lshlrev_b32_e32 v76, 16, v42
	v_and_b32_e32 v77, 0xffff0000, v42
	v_lshlrev_b32_e32 v42, 16, v43
	v_and_b32_e32 v43, 0xffff0000, v43
	v_lshlrev_b32_e32 v78, 16, v44
	v_and_b32_e32 v79, 0xffff0000, v44
	v_lshlrev_b32_e32 v44, 16, v45
	v_and_b32_e32 v45, 0xffff0000, v45
	v_lshlrev_b32_e32 v80, 16, v46
	v_and_b32_e32 v81, 0xffff0000, v46
	v_lshlrev_b32_e32 v46, 16, v47
	v_and_b32_e32 v47, 0xffff0000, v47
	v_mul_f32_e32 v57, v77, v77
	v_mul_f32_e32 v84, v43, v43
	v_mul_f32_e32 v85, v79, v79
	v_mul_f32_e32 v86, v45, v45
	v_lshlrev_b32_e32 v82, 16, v48
	v_and_b32_e32 v83, 0xffff0000, v48
	v_lshlrev_b32_e32 v48, 16, v49
	v_and_b32_e32 v49, 0xffff0000, v49
	v_mul_f32_e32 v87, v81, v81
	v_mul_f32_e32 v88, v47, v47
	v_fmac_f32_e32 v57, v76, v76
	v_fmac_f32_e32 v84, v42, v42
	v_fmac_f32_e32 v85, v78, v78
	v_fmac_f32_e32 v86, v44, v44
	v_mul_f32_e32 v89, v83, v83
	v_mul_f32_e32 v90, v49, v49
	v_fmac_f32_e32 v87, v80, v80
	v_fmac_f32_e32 v88, v46, v46
	v_add_f32_e32 v57, v57, v84
	v_add_f32_e32 v84, v85, v86
	v_fmac_f32_e32 v89, v82, v82
	v_fmac_f32_e32 v90, v48, v48
	v_add_f32_e32 v85, v87, v88
	v_add_f32_e32 v57, v57, v84
	v_add_f32_e32 v86, v89, v90
	v_add_f32_e32 v57, v57, v85
	v_add_f32_e32 v57, v57, v86
	ds_bpermute_b32 v84, v1, v57
	s_waitcnt lgkmcnt(0)
	v_add_f32_e32 v57, v57, v84
	ds_bpermute_b32 v84, v50, v57
	s_waitcnt lgkmcnt(0)
	v_add_f32_e32 v57, v57, v84
	ds_bpermute_b32 v84, v51, v57
	s_waitcnt lgkmcnt(0)
	v_add_f32_e32 v57, v57, v84
	ds_bpermute_b32 v84, v52, v57
	s_waitcnt lgkmcnt(0)
	v_add_f32_e32 v57, v57, v84
	ds_bpermute_b32 v84, v53, v57
	s_waitcnt lgkmcnt(0)
	v_add_f32_e32 v57, v57, v84
	ds_bpermute_b32 v84, v54, v57
	s_waitcnt lgkmcnt(0)
	v_add_f32_e32 v57, v57, v84
	v_fmamk_f32 v57, v57, 0x3a800000, v55
	v_mul_f32_e32 v84, 0x4f800000, v57
	v_cmp_gt_f32_e32 vcc, s5, v57
	s_nop 1
	v_cndmask_b32_e32 v57, v57, v84, vcc
	v_sqrt_f32_e32 v84, v57
	s_nop 0
	v_add_u32_e32 v85, -1, v84
	v_add_u32_e32 v86, 1, v84
	v_fma_f32 v87, -v85, v84, v57
	v_fma_f32 v88, -v86, v84, v57
	v_cmp_ge_f32_e64 s[2:3], 0, v87
	s_nop 1
	v_cndmask_b32_e64 v84, v84, v85, s[2:3]
	v_cmp_lt_f32_e64 s[2:3], 0, v88
	s_nop 1
	v_cndmask_b32_e64 v84, v84, v86, s[2:3]
	v_mul_f32_e32 v85, 0x37800000, v84
	v_cndmask_b32_e32 v84, v84, v85, vcc
	v_cmp_class_f32_e32 vcc, v57, v56
	s_nop 1
	v_cndmask_b32_e32 v57, v84, v57, vcc
	v_div_scale_f32 v84, s[2:3], v57, v57, 1.0
	v_rcp_f32_e32 v86, v84
	v_div_scale_f32 v85, vcc, 1.0, v57, 1.0
	v_fma_f32 v87, -v84, v86, 1.0
	v_fmac_f32_e32 v86, v87, v86
	v_mul_f32_e32 v87, v85, v86
	v_fma_f32 v88, -v84, v87, v85
	v_fmac_f32_e32 v87, v88, v86
	v_fma_f32 v84, -v84, v87, v85
	v_div_fmas_f32 v84, v84, v86, v87
	v_div_fixup_f32 v57, v84, v57, 1.0
	v_mul_f32_e32 v84, 0.5, v57
	v_pk_mul_f32 v[42:43], v[84:85], v[42:43] op_sel_hi:[0,1]
	v_pk_mul_f32 v[76:77], v[84:85], v[76:77] op_sel_hi:[0,1]
	v_pk_mul_f32 v[44:45], v[84:85], v[44:45] op_sel_hi:[0,1]
	v_pk_mul_f32 v[78:79], v[84:85], v[78:79] op_sel_hi:[0,1]
	v_pk_mul_f32 v[80:81], v[84:85], v[80:81] op_sel_hi:[0,1]
	v_pk_mul_f32 v[46:47], v[84:85], v[46:47] op_sel_hi:[0,1]
	v_pk_mul_f32 v[82:83], v[84:85], v[82:83] op_sel_hi:[0,1]
	v_pk_mul_f32 v[48:49], v[84:85], v[48:49] op_sel_hi:[0,1]
	v_pk_fma_f32 v[14:15], v[212:213], v[76:77], v[14:15]
	v_pk_fma_f32 v[16:17], v[214:215], v[42:43], v[16:17]
	v_pk_fma_f32 v[10:11], v[208:209], v[78:79], v[10:11]
	v_pk_fma_f32 v[12:13], v[210:211], v[44:45], v[12:13]
	v_pk_fma_f32 v[8:9], v[206:207], v[46:47], v[8:9]
	v_pk_fma_f32 v[6:7], v[204:205], v[80:81], v[6:7]
	v_pk_fma_f32 v[4:5], v[202:203], v[48:49], v[4:5]
	v_pk_fma_f32 v[2:3], v[200:201], v[82:83], v[2:3]
	v_pk_mul_f32 v[18:19], v[16:17], v[16:17]
	v_pk_mul_f32 v[20:21], v[14:15], v[14:15]
	v_pk_mul_f32 v[22:23], v[12:13], v[12:13]
	v_pk_mul_f32 v[24:25], v[10:11], v[10:11]
	v_pk_mov_b32 v[30:31], v[20:21], v[18:19] op_sel:[1,0]
	v_mov_b32_e32 v21, v19
	v_pk_mov_b32 v[18:19], v[24:25], v[22:23] op_sel:[1,0]
	v_mov_b32_e32 v25, v23
	v_mul_f32_e32 v26, v6, v6
	v_mul_f32_e32 v28, v8, v8
	v_pk_add_f32 v[20:21], v[30:31], v[20:21]
	v_pk_add_f32 v[18:19], v[18:19], v[24:25]
	v_pk_fma_f32 v[22:23], v[6:7], v[6:7], v[26:27] op_sel_hi:[1,1,0]
	v_pk_fma_f32 v[26:27], v[8:9], v[8:9], v[28:29] op_sel_hi:[1,1,0]
	v_pk_add_f32 v[20:21], v[20:21], v[20:21] op_sel_hi:[0,1]
	v_pk_add_f32 v[18:19], v[18:19], v[18:19] op_sel_hi:[0,1]
	v_mul_f32_e32 v22, v2, v2
	v_mul_f32_e32 v26, v3, v3
	v_mul_f32_e32 v20, v4, v4
	v_mul_f32_e32 v18, v5, v5
	v_pk_add_f32 v[22:23], v[22:23], v[26:27]
	v_pk_add_f32 v[18:19], v[20:21], v[18:19]
	s_nop 0
	v_pk_add_f32 v[18:19], v[22:23], v[18:19]
	s_nop 0
	v_add_f32_e32 v18, v18, v19
	ds_bpermute_b32 v19, v1, v18
	s_waitcnt lgkmcnt(0)
	v_add_f32_e32 v18, v18, v19
	ds_bpermute_b32 v19, v50, v18
	s_waitcnt lgkmcnt(0)
	v_add_f32_e32 v18, v18, v19
	ds_bpermute_b32 v19, v51, v18
	s_waitcnt lgkmcnt(0)
	v_add_f32_e32 v18, v18, v19
	ds_bpermute_b32 v19, v52, v18
	s_waitcnt lgkmcnt(0)
	v_add_f32_e32 v18, v18, v19
	ds_bpermute_b32 v19, v53, v18
	s_waitcnt lgkmcnt(0)
	v_add_f32_e32 v18, v18, v19
	ds_bpermute_b32 v19, v54, v18
	s_waitcnt lgkmcnt(0)
	v_add_f32_e32 v18, v18, v19
	v_fmamk_f32 v18, v18, 0x3a800000, v55
	v_mul_f32_e32 v19, 0x4f800000, v18
	v_cmp_gt_f32_e32 vcc, s5, v18
	s_nop 1
	v_cndmask_b32_e32 v18, v18, v19, vcc
	v_sqrt_f32_e32 v19, v18
	s_nop 0
	v_add_u32_e32 v20, -1, v19
	v_add_u32_e32 v21, 1, v19
	v_fma_f32 v22, -v20, v19, v18
	v_fma_f32 v23, -v21, v19, v18
	v_cmp_ge_f32_e64 s[2:3], 0, v22
	s_nop 1
	v_cndmask_b32_e64 v19, v19, v20, s[2:3]
	v_cmp_lt_f32_e64 s[2:3], 0, v23
	s_nop 1
	v_cndmask_b32_e64 v19, v19, v21, s[2:3]
	v_mul_f32_e32 v20, 0x37800000, v19
	v_cndmask_b32_e32 v19, v19, v20, vcc
	v_cmp_class_f32_e32 vcc, v18, v56
	s_nop 1
	v_cndmask_b32_e32 v18, v19, v18, vcc
	v_div_scale_f32 v19, s[2:3], v18, v18, 1.0
	v_rcp_f32_e32 v21, v19
	v_div_scale_f32 v20, vcc, 1.0, v18, 1.0
	v_fma_f32 v22, -v19, v21, 1.0
	v_fmac_f32_e32 v21, v22, v21
	v_mul_f32_e32 v22, v20, v21
	v_fma_f32 v23, -v19, v22, v20
	v_fmac_f32_e32 v22, v23, v21
	v_fma_f32 v19, -v19, v22, v20
	v_div_fmas_f32 v19, v19, v21, v22
	v_div_fixup_f32 v18, v19, v18, 1.0
	v_pk_mul_f32 v[14:15], v[14:15], v[18:19] op_sel_hi:[1,0]
	v_pk_mul_f32 v[16:17], v[16:17], v[18:19] op_sel_hi:[1,0]
	v_pk_mul_f32 v[10:11], v[10:11], v[18:19] op_sel_hi:[1,0]
	v_pk_mul_f32 v[12:13], v[12:13], v[18:19] op_sel_hi:[1,0]
	v_pk_mul_f32 v[6:7], v[6:7], v[18:19] op_sel_hi:[1,0]
	v_pk_mul_f32 v[8:9], v[8:9], v[18:19] op_sel_hi:[1,0]
	v_pk_mul_f32 v[2:3], v[2:3], v[18:19] op_sel_hi:[1,0]
	v_pk_mul_f32 v[4:5], v[4:5], v[18:19] op_sel_hi:[1,0]
	v_pk_mul_f32 v[16:17], v[60:61], v[16:17]
	v_pk_mul_f32 v[14:15], v[58:59], v[14:15]
	v_pk_mul_f32 v[12:13], v[64:65], v[12:13]
	v_pk_mul_f32 v[10:11], v[62:63], v[10:11]
	v_pk_mul_f32 v[8:9], v[68:69], v[8:9]
	v_pk_mul_f32 v[6:7], v[66:67], v[6:7]
	v_pk_mul_f32 v[4:5], v[72:73], v[4:5]
	v_pk_mul_f32 v[2:3], v[70:71], v[2:3]
	v_cvt_pk_bf16_f32 v14, v14, v15
	v_cvt_pk_bf16_f32 v15, v16, v17
	v_cvt_pk_bf16_f32 v10, v10, v11
	v_cvt_pk_bf16_f32 v11, v12, v13
	v_cvt_pk_bf16_f32 v6, v6, v7
	v_cvt_pk_bf16_f32 v7, v8, v9
	v_cvt_pk_bf16_f32 v2, v2, v3
	v_cvt_pk_bf16_f32 v3, v4, v5
	global_store_dwordx2 v[74:75], v[14:15], off offset:-1536
	global_store_dwordx2 v[74:75], v[10:11], off offset:-1024
	global_store_dwordx2 v[74:75], v[6:7], off offset:-512
	global_store_dwordx2 v[74:75], v[2:3], off
	s_branch .LBB0_174
.Lp3_tailB:
	s_waitcnt vmcnt(0)
	v_lshlrev_b32_e32 v176, 16, v142
	v_and_b32_e32 v177, 0xffff0000, v142
	v_lshlrev_b32_e32 v142, 16, v143
	v_and_b32_e32 v143, 0xffff0000, v143
	v_lshlrev_b32_e32 v178, 16, v144
	v_and_b32_e32 v179, 0xffff0000, v144
	v_lshlrev_b32_e32 v144, 16, v145
	v_and_b32_e32 v145, 0xffff0000, v145
	v_lshlrev_b32_e32 v180, 16, v146
	v_and_b32_e32 v181, 0xffff0000, v146
	v_lshlrev_b32_e32 v146, 16, v147
	v_and_b32_e32 v147, 0xffff0000, v147
	v_mul_f32_e32 v157, v177, v177
	v_mul_f32_e32 v184, v143, v143
	v_mul_f32_e32 v185, v179, v179
	v_mul_f32_e32 v186, v145, v145
	v_lshlrev_b32_e32 v182, 16, v148
	v_and_b32_e32 v183, 0xffff0000, v148
	v_lshlrev_b32_e32 v148, 16, v149
	v_and_b32_e32 v149, 0xffff0000, v149
	v_mul_f32_e32 v187, v181, v181
	v_mul_f32_e32 v188, v147, v147
	v_fmac_f32_e32 v157, v176, v176
	v_fmac_f32_e32 v184, v142, v142
	v_fmac_f32_e32 v185, v178, v178
	v_fmac_f32_e32 v186, v144, v144
	v_mul_f32_e32 v189, v183, v183
	v_mul_f32_e32 v190, v149, v149
	v_fmac_f32_e32 v187, v180, v180
	v_fmac_f32_e32 v188, v146, v146
	v_add_f32_e32 v157, v157, v184
	v_add_f32_e32 v184, v185, v186
	v_fmac_f32_e32 v189, v182, v182
	v_fmac_f32_e32 v190, v148, v148
	v_add_f32_e32 v185, v187, v188
	v_add_f32_e32 v157, v157, v184
	v_add_f32_e32 v186, v189, v190
	v_add_f32_e32 v157, v157, v185
	v_add_f32_e32 v157, v157, v186
	ds_bpermute_b32 v184, v1, v157
	s_waitcnt lgkmcnt(0)
	v_add_f32_e32 v157, v157, v184
	ds_bpermute_b32 v184, v50, v157
	s_waitcnt lgkmcnt(0)
	v_add_f32_e32 v157, v157, v184
	ds_bpermute_b32 v184, v51, v157
	s_waitcnt lgkmcnt(0)
	v_add_f32_e32 v157, v157, v184
	ds_bpermute_b32 v184, v52, v157
	s_waitcnt lgkmcnt(0)
	v_add_f32_e32 v157, v157, v184
	ds_bpermute_b32 v184, v53, v157
	s_waitcnt lgkmcnt(0)
	v_add_f32_e32 v157, v157, v184
	ds_bpermute_b32 v184, v54, v157
	s_waitcnt lgkmcnt(0)
	v_add_f32_e32 v157, v157, v184
	v_fmamk_f32 v157, v157, 0x3a800000, v55
	v_mul_f32_e32 v184, 0x4f800000, v157
	v_cmp_gt_f32_e32 vcc, s5, v157
	s_nop 1
	v_cndmask_b32_e32 v157, v157, v184, vcc
	v_sqrt_f32_e32 v184, v157
	s_nop 0
	v_add_u32_e32 v185, -1, v184
	v_add_u32_e32 v186, 1, v184
	v_fma_f32 v187, -v185, v184, v157
	v_fma_f32 v188, -v186, v184, v157
	v_cmp_ge_f32_e64 s[2:3], 0, v187
	s_nop 1
	v_cndmask_b32_e64 v184, v184, v185, s[2:3]
	v_cmp_lt_f32_e64 s[2:3], 0, v188
	s_nop 1
	v_cndmask_b32_e64 v184, v184, v186, s[2:3]
	v_mul_f32_e32 v185, 0x37800000, v184
	v_cndmask_b32_e32 v184, v184, v185, vcc
	v_cmp_class_f32_e32 vcc, v157, v56
	s_nop 1
	v_cndmask_b32_e32 v157, v184, v157, vcc
	v_div_scale_f32 v184, s[2:3], v157, v157, 1.0
	v_rcp_f32_e32 v186, v184
	v_div_scale_f32 v185, vcc, 1.0, v157, 1.0
	v_fma_f32 v187, -v184, v186, 1.0
	v_fmac_f32_e32 v186, v187, v186
	v_mul_f32_e32 v187, v185, v186
	v_fma_f32 v188, -v184, v187, v185
	v_fmac_f32_e32 v187, v188, v186
	v_fma_f32 v184, -v184, v187, v185
	v_div_fmas_f32 v184, v184, v186, v187
	v_div_fixup_f32 v157, v184, v157, 1.0
	v_mul_f32_e32 v184, 0.5, v157
	v_pk_mul_f32 v[142:143], v[184:185], v[142:143] op_sel_hi:[0,1]
	v_pk_mul_f32 v[176:177], v[184:185], v[176:177] op_sel_hi:[0,1]
	v_pk_mul_f32 v[144:145], v[184:185], v[144:145] op_sel_hi:[0,1]
	v_pk_mul_f32 v[178:179], v[184:185], v[178:179] op_sel_hi:[0,1]
	v_pk_mul_f32 v[180:181], v[184:185], v[180:181] op_sel_hi:[0,1]
	v_pk_mul_f32 v[146:147], v[184:185], v[146:147] op_sel_hi:[0,1]
	v_pk_mul_f32 v[182:183], v[184:185], v[182:183] op_sel_hi:[0,1]
	v_pk_mul_f32 v[148:149], v[184:185], v[148:149] op_sel_hi:[0,1]
	v_pk_fma_f32 v[114:115], v[212:213], v[176:177], v[114:115]
	v_pk_fma_f32 v[116:117], v[214:215], v[142:143], v[116:117]
	v_pk_fma_f32 v[110:111], v[208:209], v[178:179], v[110:111]
	v_pk_fma_f32 v[112:113], v[210:211], v[144:145], v[112:113]
	v_pk_fma_f32 v[108:109], v[206:207], v[146:147], v[108:109]
	v_pk_fma_f32 v[106:107], v[204:205], v[180:181], v[106:107]
	v_pk_fma_f32 v[104:105], v[202:203], v[148:149], v[104:105]
	v_pk_fma_f32 v[102:103], v[200:201], v[182:183], v[102:103]
	v_pk_mul_f32 v[118:119], v[116:117], v[116:117]
	v_pk_mul_f32 v[120:121], v[114:115], v[114:115]
	v_pk_mul_f32 v[122:123], v[112:113], v[112:113]
	v_pk_mul_f32 v[124:125], v[110:111], v[110:111]
	v_pk_mov_b32 v[130:131], v[120:121], v[118:119] op_sel:[1,0]
	v_mov_b32_e32 v121, v119
	v_pk_mov_b32 v[118:119], v[124:125], v[122:123] op_sel:[1,0]
	v_mov_b32_e32 v125, v123
	v_mul_f32_e32 v126, v106, v106
	v_mul_f32_e32 v128, v108, v108
	v_pk_add_f32 v[120:121], v[130:131], v[120:121]
	v_pk_add_f32 v[118:119], v[118:119], v[124:125]
	v_pk_fma_f32 v[122:123], v[106:107], v[106:107], v[126:127] op_sel_hi:[1,1,0]
	v_pk_fma_f32 v[126:127], v[108:109], v[108:109], v[128:129] op_sel_hi:[1,1,0]
	v_pk_add_f32 v[120:121], v[120:121], v[120:121] op_sel_hi:[0,1]
	v_pk_add_f32 v[118:119], v[118:119], v[118:119] op_sel_hi:[0,1]
	v_mul_f32_e32 v122, v102, v102
	v_mul_f32_e32 v126, v103, v103
	v_mul_f32_e32 v120, v104, v104
	v_mul_f32_e32 v118, v105, v105
	v_pk_add_f32 v[122:123], v[122:123], v[126:127]
	v_pk_add_f32 v[118:119], v[120:121], v[118:119]
	s_nop 0
	v_pk_add_f32 v[118:119], v[122:123], v[118:119]
	s_nop 0
	v_add_f32_e32 v118, v118, v119
	ds_bpermute_b32 v119, v1, v118
	s_waitcnt lgkmcnt(0)
	v_add_f32_e32 v118, v118, v119
	ds_bpermute_b32 v119, v50, v118
	s_waitcnt lgkmcnt(0)
	v_add_f32_e32 v118, v118, v119
	ds_bpermute_b32 v119, v51, v118
	s_waitcnt lgkmcnt(0)
	v_add_f32_e32 v118, v118, v119
	ds_bpermute_b32 v119, v52, v118
	s_waitcnt lgkmcnt(0)
	v_add_f32_e32 v118, v118, v119
	ds_bpermute_b32 v119, v53, v118
	s_waitcnt lgkmcnt(0)
	v_add_f32_e32 v118, v118, v119
	ds_bpermute_b32 v119, v54, v118
	s_waitcnt lgkmcnt(0)
	v_add_f32_e32 v118, v118, v119
	v_fmamk_f32 v118, v118, 0x3a800000, v55
	v_mul_f32_e32 v119, 0x4f800000, v118
	v_cmp_gt_f32_e32 vcc, s5, v118
	s_nop 1
	v_cndmask_b32_e32 v118, v118, v119, vcc
	v_sqrt_f32_e32 v119, v118
	s_nop 0
	v_add_u32_e32 v120, -1, v119
	v_add_u32_e32 v121, 1, v119
	v_fma_f32 v122, -v120, v119, v118
	v_fma_f32 v123, -v121, v119, v118
	v_cmp_ge_f32_e64 s[2:3], 0, v122
	s_nop 1
	v_cndmask_b32_e64 v119, v119, v120, s[2:3]
	v_cmp_lt_f32_e64 s[2:3], 0, v123
	s_nop 1
	v_cndmask_b32_e64 v119, v119, v121, s[2:3]
	v_mul_f32_e32 v120, 0x37800000, v119
	v_cndmask_b32_e32 v119, v119, v120, vcc
	v_cmp_class_f32_e32 vcc, v118, v56
	s_nop 1
	v_cndmask_b32_e32 v118, v119, v118, vcc
	v_div_scale_f32 v119, s[2:3], v118, v118, 1.0
	v_rcp_f32_e32 v121, v119
	v_div_scale_f32 v120, vcc, 1.0, v118, 1.0
	v_fma_f32 v122, -v119, v121, 1.0
	v_fmac_f32_e32 v121, v122, v121
	v_mul_f32_e32 v122, v120, v121
	v_fma_f32 v123, -v119, v122, v120
	v_fmac_f32_e32 v122, v123, v121
	v_fma_f32 v119, -v119, v122, v120
	v_div_fmas_f32 v119, v119, v121, v122
	v_div_fixup_f32 v118, v119, v118, 1.0
	v_pk_mul_f32 v[114:115], v[114:115], v[118:119] op_sel_hi:[1,0]
	v_pk_mul_f32 v[116:117], v[116:117], v[118:119] op_sel_hi:[1,0]
	v_pk_mul_f32 v[110:111], v[110:111], v[118:119] op_sel_hi:[1,0]
	v_pk_mul_f32 v[112:113], v[112:113], v[118:119] op_sel_hi:[1,0]
	v_pk_mul_f32 v[106:107], v[106:107], v[118:119] op_sel_hi:[1,0]
	v_pk_mul_f32 v[108:109], v[108:109], v[118:119] op_sel_hi:[1,0]
	v_pk_mul_f32 v[102:103], v[102:103], v[118:119] op_sel_hi:[1,0]
	v_pk_mul_f32 v[104:105], v[104:105], v[118:119] op_sel_hi:[1,0]
	v_pk_mul_f32 v[116:117], v[60:61], v[116:117]
	v_pk_mul_f32 v[114:115], v[58:59], v[114:115]
	v_pk_mul_f32 v[112:113], v[64:65], v[112:113]
	v_pk_mul_f32 v[110:111], v[62:63], v[110:111]
	v_pk_mul_f32 v[108:109], v[68:69], v[108:109]
	v_pk_mul_f32 v[106:107], v[66:67], v[106:107]
	v_pk_mul_f32 v[104:105], v[72:73], v[104:105]
	v_pk_mul_f32 v[102:103], v[70:71], v[102:103]
	v_cvt_pk_bf16_f32 v114, v114, v115
	v_cvt_pk_bf16_f32 v115, v116, v117
	v_cvt_pk_bf16_f32 v110, v110, v111
	v_cvt_pk_bf16_f32 v111, v112, v113
	v_cvt_pk_bf16_f32 v106, v106, v107
	v_cvt_pk_bf16_f32 v107, v108, v109
	v_cvt_pk_bf16_f32 v102, v102, v103
	v_cvt_pk_bf16_f32 v103, v104, v105
	global_store_dwordx2 v[174:175], v[114:115], off offset:-1536
	global_store_dwordx2 v[174:175], v[110:111], off offset:-1024
	global_store_dwordx2 v[174:175], v[106:107], off offset:-512
	global_store_dwordx2 v[174:175], v[102:103], off

.LBB0_732:
	global_load_dwordx4 v[30:33], v[8:9], off
	global_load_dwordx4 v[34:37], v[8:9], off offset:1024
	global_load_dwordx4 v[38:41], v[8:9], off offset:2048
	global_load_dwordx4 v[42:45], v[8:9], off offset:3072
	global_load_dwordx2 v[46:47], v[10:11], off offset:-1536
	global_load_dwordx2 v[48:49], v[10:11], off offset:-1024
	global_load_dwordx2 v[50:51], v[10:11], off offset:-512
	global_load_dwordx2 v[52:53], v[10:11], off
	global_load_dwordx4 v[22:25], v[12:13], off offset:-2048
	global_load_dwordx4 v[26:29], v[12:13], off offset:-1024
	global_load_dwordx4 v[4:7], v[12:13], off
	global_load_dwordx4 v[0:3], v[12:13], off offset:1024
	v_mov_b32_e32 v70, v12
	v_mov_b32_e32 v71, v13
	s_add_i32 s2, s2, s8
	v_lshl_add_u64 v[10:11], v[10:11], 0, s[4:5]
	v_lshl_add_u64 v[12:13], v[12:13], 0, s[6:7]
	s_cmp_lt_i32 s2, 0x8000
	s_cbranch_scc0 .Lp11_tailA
	global_load_dwordx2 v[146:147], v[10:11], off offset:-1536
	global_load_dwordx2 v[148:149], v[10:11], off offset:-1024
	global_load_dwordx2 v[150:151], v[10:11], off offset:-512
	global_load_dwordx2 v[152:153], v[10:11], off
	global_load_dwordx4 v[122:125], v[12:13], off offset:-2048
	global_load_dwordx4 v[126:129], v[12:13], off offset:-1024
	global_load_dwordx4 v[104:107], v[12:13], off
	global_load_dwordx4 v[100:103], v[12:13], off offset:1024
	s_waitcnt vmcnt(8)
	s_branch .Lp11_compA
.Lp11_loop:
	v_mov_b32_e32 v70, v12
	v_mov_b32_e32 v71, v13
	s_add_i32 s2, s2, s8
	v_lshl_add_u64 v[10:11], v[10:11], 0, s[4:5]
	v_lshl_add_u64 v[12:13], v[12:13], 0, s[6:7]
	s_cmp_lt_i32 s2, 0x8000
	s_cbranch_scc0 .Lp11_tailA
	global_load_dwordx2 v[146:147], v[10:11], off offset:-1536
	global_load_dwordx2 v[148:149], v[10:11], off offset:-1024
	global_load_dwordx2 v[150:151], v[10:11], off offset:-512
	global_load_dwordx2 v[152:153], v[10:11], off
	global_load_dwordx4 v[122:125], v[12:13], off offset:-2048
	global_load_dwordx4 v[126:129], v[12:13], off offset:-1024
	global_load_dwordx4 v[104:107], v[12:13], off
	global_load_dwordx4 v[100:103], v[12:13], off offset:1024
	s_waitcnt vmcnt(12)
.Lp11_compA:
	v_lshlrev_b32_e32 v54, 16, v46
	v_and_b32_e32 v55, 0xffff0000, v46
	v_lshlrev_b32_e32 v46, 16, v47
	v_and_b32_e32 v47, 0xffff0000, v47
	v_lshlrev_b32_e32 v56, 16, v48
	v_and_b32_e32 v57, 0xffff0000, v48
	v_lshlrev_b32_e32 v48, 16, v49
	v_and_b32_e32 v49, 0xffff0000, v49
	v_lshlrev_b32_e32 v58, 16, v50
	v_and_b32_e32 v59, 0xffff0000, v50
	v_lshlrev_b32_e32 v50, 16, v51
	v_and_b32_e32 v51, 0xffff0000, v51
	v_mul_f32_e32 v62, v55, v55
	v_mul_f32_e32 v63, v47, v47
	v_mul_f32_e32 v64, v57, v57
	v_mul_f32_e32 v65, v49, v49
	v_lshlrev_b32_e32 v60, 16, v52
	v_and_b32_e32 v61, 0xffff0000, v52
	v_lshlrev_b32_e32 v52, 16, v53
	v_and_b32_e32 v53, 0xffff0000, v53
	v_mul_f32_e32 v66, v59, v59
	v_mul_f32_e32 v67, v51, v51
	v_fmac_f32_e32 v62, v54, v54
	v_fmac_f32_e32 v63, v46, v46
	v_fmac_f32_e32 v64, v56, v56
	v_fmac_f32_e32 v65, v48, v48
	v_mul_f32_e32 v68, v61, v61
	v_mul_f32_e32 v69, v53, v53
	v_fmac_f32_e32 v66, v58, v58
	v_fmac_f32_e32 v67, v50, v50
	v_add_f32_e32 v62, v62, v63
	v_add_f32_e32 v63, v64, v65
	v_fmac_f32_e32 v68, v60, v60
	v_fmac_f32_e32 v69, v52, v52
	v_add_f32_e32 v64, v66, v67
	v_add_f32_e32 v62, v62, v63
	v_add_f32_e32 v65, v68, v69
	v_add_f32_e32 v62, v62, v64
	v_add_f32_e32 v62, v62, v65
	ds_bpermute_b32 v63, v14, v62
	s_waitcnt lgkmcnt(0)
	v_add_f32_e32 v62, v62, v63
	ds_bpermute_b32 v63, v15, v62
	s_waitcnt lgkmcnt(0)
	v_add_f32_e32 v62, v62, v63
	ds_bpermute_b32 v63, v16, v62
	s_waitcnt lgkmcnt(0)
	v_add_f32_e32 v62, v62, v63
	ds_bpermute_b32 v63, v17, v62
	s_waitcnt lgkmcnt(0)
	v_add_f32_e32 v62, v62, v63
	ds_bpermute_b32 v63, v18, v62
	s_waitcnt lgkmcnt(0)
	v_add_f32_e32 v62, v62, v63
	ds_bpermute_b32 v63, v19, v62
	s_waitcnt lgkmcnt(0)
	v_add_f32_e32 v62, v62, v63
	v_fmamk_f32 v62, v62, 0x3a800000, v20
	v_mul_f32_e32 v63, 0x4f800000, v62
	v_cmp_gt_f32_e32 vcc, s3, v62
	s_nop 1
	v_cndmask_b32_e32 v62, v62, v63, vcc
	v_sqrt_f32_e32 v63, v62
	s_nop 0
	v_add_u32_e32 v64, -1, v63
	v_add_u32_e32 v65, 1, v63
	v_fma_f32 v66, -v64, v63, v62
	v_fma_f32 v67, -v65, v63, v62
	v_cmp_ge_f32_e64 s[0:1], 0, v66
	s_nop 1
	v_cndmask_b32_e64 v63, v63, v64, s[0:1]
	v_cmp_lt_f32_e64 s[0:1], 0, v67
	s_nop 1
	v_cndmask_b32_e64 v63, v63, v65, s[0:1]
	v_mul_f32_e32 v64, 0x37800000, v63
	v_cndmask_b32_e32 v63, v63, v64, vcc
	v_cmp_class_f32_e32 vcc, v62, v21
	s_nop 1
	v_cndmask_b32_e32 v62, v63, v62, vcc
	v_div_scale_f32 v63, s[0:1], v62, v62, 1.0
	v_rcp_f32_e32 v65, v63
	v_div_scale_f32 v64, vcc, 1.0, v62, 1.0
	v_fma_f32 v66, -v63, v65, 1.0
	v_fmac_f32_e32 v65, v66, v65
	v_mul_f32_e32 v66, v64, v65
	v_fma_f32 v67, -v63, v66, v64
	v_fmac_f32_e32 v66, v67, v65
	v_fma_f32 v63, -v63, v66, v64
	v_div_fmas_f32 v63, v63, v65, v66
	v_div_fixup_f32 v62, v63, v62, 1.0
	v_mul_f32_e32 v62, 0.5, v62
	v_pk_mul_f32 v[54:55], v[62:63], v[54:55] op_sel_hi:[0,1]
	v_pk_mul_f32 v[46:47], v[62:63], v[46:47] op_sel_hi:[0,1]
	v_pk_mul_f32 v[56:57], v[62:63], v[56:57] op_sel_hi:[0,1]
	v_pk_mul_f32 v[48:49], v[62:63], v[48:49] op_sel_hi:[0,1]
	v_pk_mul_f32 v[58:59], v[62:63], v[58:59] op_sel_hi:[0,1]
	v_pk_mul_f32 v[50:51], v[62:63], v[50:51] op_sel_hi:[0,1]
	v_pk_mul_f32 v[60:61], v[62:63], v[60:61] op_sel_hi:[0,1]
	v_pk_mul_f32 v[52:53], v[62:63], v[52:53] op_sel_hi:[0,1]
	v_pk_fma_f32 v[24:25], v[32:33], v[46:47], v[24:25]
	v_pk_fma_f32 v[22:23], v[30:31], v[54:55], v[22:23]
	v_pk_fma_f32 v[28:29], v[36:37], v[48:49], v[28:29]
	v_pk_fma_f32 v[26:27], v[34:35], v[56:57], v[26:27]
	v_pk_fma_f32 v[6:7], v[40:41], v[50:51], v[6:7]
	v_pk_fma_f32 v[4:5], v[38:39], v[58:59], v[4:5]
	v_pk_fma_f32 v[2:3], v[44:45], v[52:53], v[2:3]
	v_pk_fma_f32 v[0:1], v[42:43], v[60:61], v[0:1]
	global_store_dwordx4 v[70:71], v[22:25], off offset:-2048
	global_store_dwordx4 v[70:71], v[26:29], off offset:-1024
	global_store_dwordx4 v[70:71], v[4:7], off
	global_store_dwordx4 v[70:71], v[0:3], off offset:1024
	v_mov_b32_e32 v170, v12
	v_mov_b32_e32 v171, v13
	s_add_i32 s2, s2, s8
	v_lshl_add_u64 v[10:11], v[10:11], 0, s[4:5]
	v_lshl_add_u64 v[12:13], v[12:13], 0, s[6:7]
	s_cmp_lt_i32 s2, 0x8000
	s_cbranch_scc0 .Lp11_tailB
	global_load_dwordx2 v[46:47], v[10:11], off offset:-1536
	global_load_dwordx2 v[48:49], v[10:11], off offset:-1024
	global_load_dwordx2 v[50:51], v[10:11], off offset:-512
	global_load_dwordx2 v[52:53], v[10:11], off
	global_load_dwordx4 v[22:25], v[12:13], off offset:-2048
	global_load_dwordx4 v[26:29], v[12:13], off offset:-1024
	global_load_dwordx4 v[4:7], v[12:13], off
	global_load_dwordx4 v[0:3], v[12:13], off offset:1024
	s_waitcnt vmcnt(12)
	v_lshlrev_b32_e32 v154, 16, v146
	v_and_b32_e32 v155, 0xffff0000, v146
	v_lshlrev_b32_e32 v146, 16, v147
	v_and_b32_e32 v147, 0xffff0000, v147
	v_lshlrev_b32_e32 v156, 16, v148
	v_and_b32_e32 v157, 0xffff0000, v148
	v_lshlrev_b32_e32 v148, 16, v149
	v_and_b32_e32 v149, 0xffff0000, v149
	v_lshlrev_b32_e32 v158, 16, v150
	v_and_b32_e32 v159, 0xffff0000, v150
	v_lshlrev_b32_e32 v150, 16, v151
	v_and_b32_e32 v151, 0xffff0000, v151
	v_mul_f32_e32 v162, v155, v155
	v_mul_f32_e32 v163, v147, v147
	v_mul_f32_e32 v164, v157, v157
	v_mul_f32_e32 v165, v149, v149
	v_lshlrev_b32_e32 v160, 16, v152
	v_and_b32_e32 v161, 0xffff0000, v152
	v_lshlrev_b32_e32 v152, 16, v153
	v_and_b32_e32 v153, 0xffff0000, v153
	v_mul_f32_e32 v166, v159, v159
	v_mul_f32_e32 v167, v151, v151
	v_fmac_f32_e32 v162, v154, v154
	v_fmac_f32_e32 v163, v146, v146
	v_fmac_f32_e32 v164, v156, v156
	v_fmac_f32_e32 v165, v148, v148
	v_mul_f32_e32 v168, v161, v161
	v_mul_f32_e32 v169, v153, v153
	v_fmac_f32_e32 v166, v158, v158
	v_fmac_f32_e32 v167, v150, v150
	v_add_f32_e32 v162, v162, v163
	v_add_f32_e32 v163, v164, v165
	v_fmac_f32_e32 v168, v160, v160
	v_fmac_f32_e32 v169, v152, v152
	v_add_f32_e32 v164, v166, v167
	v_add_f32_e32 v162, v162, v163
	v_add_f32_e32 v165, v168, v169
	v_add_f32_e32 v162, v162, v164
	v_add_f32_e32 v162, v162, v165
	ds_bpermute_b32 v163, v14, v162
	s_waitcnt lgkmcnt(0)
	v_add_f32_e32 v162, v162, v163
	ds_bpermute_b32 v163, v15, v162
	s_waitcnt lgkmcnt(0)
	v_add_f32_e32 v162, v162, v163
	ds_bpermute_b32 v163, v16, v162
	s_waitcnt lgkmcnt(0)
	v_add_f32_e32 v162, v162, v163
	ds_bpermute_b32 v163, v17, v162
	s_waitcnt lgkmcnt(0)
	v_add_f32_e32 v162, v162, v163
	ds_bpermute_b32 v163, v18, v162
	s_waitcnt lgkmcnt(0)
	v_add_f32_e32 v162, v162, v163
	ds_bpermute_b32 v163, v19, v162
	s_waitcnt lgkmcnt(0)
	v_add_f32_e32 v162, v162, v163
	v_fmamk_f32 v162, v162, 0x3a800000, v20
	v_mul_f32_e32 v163, 0x4f800000, v162
	v_cmp_gt_f32_e32 vcc, s3, v162
	s_nop 1
	v_cndmask_b32_e32 v162, v162, v163, vcc
	v_sqrt_f32_e32 v163, v162
	s_nop 0
	v_add_u32_e32 v164, -1, v163
	v_add_u32_e32 v165, 1, v163
	v_fma_f32 v166, -v164, v163, v162
	v_fma_f32 v167, -v165, v163, v162
	v_cmp_ge_f32_e64 s[0:1], 0, v166
	s_nop 1
	v_cndmask_b32_e64 v163, v163, v164, s[0:1]
	v_cmp_lt_f32_e64 s[0:1], 0, v167
	s_nop 1
	v_cndmask_b32_e64 v163, v163, v165, s[0:1]
	v_mul_f32_e32 v164, 0x37800000, v163
	v_cndmask_b32_e32 v163, v163, v164, vcc
	v_cmp_class_f32_e32 vcc, v162, v21
	s_nop 1
	v_cndmask_b32_e32 v162, v163, v162, vcc
	v_div_scale_f32 v163, s[0:1], v162, v162, 1.0
	v_rcp_f32_e32 v165, v163
	v_div_scale_f32 v164, vcc, 1.0, v162, 1.0
	v_fma_f32 v166, -v163, v165, 1.0
	v_fmac_f32_e32 v165, v166, v165
	v_mul_f32_e32 v166, v164, v165
	v_fma_f32 v167, -v163, v166, v164
	v_fmac_f32_e32 v166, v167, v165
	v_fma_f32 v163, -v163, v166, v164
	v_div_fmas_f32 v163, v163, v165, v166
	v_div_fixup_f32 v162, v163, v162, 1.0
	v_mul_f32_e32 v162, 0.5, v162
	v_pk_mul_f32 v[154:155], v[162:163], v[154:155] op_sel_hi:[0,1]
	v_pk_mul_f32 v[146:147], v[162:163], v[146:147] op_sel_hi:[0,1]
	v_pk_mul_f32 v[156:157], v[162:163], v[156:157] op_sel_hi:[0,1]
	v_pk_mul_f32 v[148:149], v[162:163], v[148:149] op_sel_hi:[0,1]
	v_pk_mul_f32 v[158:159], v[162:163], v[158:159] op_sel_hi:[0,1]
	v_pk_mul_f32 v[150:151], v[162:163], v[150:151] op_sel_hi:[0,1]
	v_pk_mul_f32 v[160:161], v[162:163], v[160:161] op_sel_hi:[0,1]
	v_pk_mul_f32 v[152:153], v[162:163], v[152:153] op_sel_hi:[0,1]
	v_pk_fma_f32 v[124:125], v[32:33], v[146:147], v[124:125]
	v_pk_fma_f32 v[122:123], v[30:31], v[154:155], v[122:123]
	v_pk_fma_f32 v[128:129], v[36:37], v[148:149], v[128:129]
	v_pk_fma_f32 v[126:127], v[34:35], v[156:157], v[126:127]
	v_pk_fma_f32 v[106:107], v[40:41], v[150:151], v[106:107]
	v_pk_fma_f32 v[104:105], v[38:39], v[158:159], v[104:105]
	v_pk_fma_f32 v[102:103], v[44:45], v[152:153], v[102:103]
	v_pk_fma_f32 v[100:101], v[42:43], v[160:161], v[100:101]
	global_store_dwordx4 v[170:171], v[122:125], off offset:-2048
	global_store_dwordx4 v[170:171], v[126:129], off offset:-1024
	global_store_dwordx4 v[170:171], v[104:107], off
	global_store_dwordx4 v[170:171], v[100:103], off offset:1024
	s_branch .Lp11_loop
.Lp11_tailA:
	s_waitcnt vmcnt(0)
	v_lshlrev_b32_e32 v54, 16, v46
	v_and_b32_e32 v55, 0xffff0000, v46
	v_lshlrev_b32_e32 v46, 16, v47
	v_and_b32_e32 v47, 0xffff0000, v47
	v_lshlrev_b32_e32 v56, 16, v48
	v_and_b32_e32 v57, 0xffff0000, v48
	v_lshlrev_b32_e32 v48, 16, v49
	v_and_b32_e32 v49, 0xffff0000, v49
	v_lshlrev_b32_e32 v58, 16, v50
	v_and_b32_e32 v59, 0xffff0000, v50
	v_lshlrev_b32_e32 v50, 16, v51
	v_and_b32_e32 v51, 0xffff0000, v51
	v_mul_f32_e32 v62, v55, v55
	v_mul_f32_e32 v63, v47, v47
	v_mul_f32_e32 v64, v57, v57
	v_mul_f32_e32 v65, v49, v49
	v_lshlrev_b32_e32 v60, 16, v52
	v_and_b32_e32 v61, 0xffff0000, v52
	v_lshlrev_b32_e32 v52, 16, v53
	v_and_b32_e32 v53, 0xffff0000, v53
	v_mul_f32_e32 v66, v59, v59
	v_mul_f32_e32 v67, v51, v51
	v_fmac_f32_e32 v62, v54, v54
	v_fmac_f32_e32 v63, v46, v46
	v_fmac_f32_e32 v64, v56, v56
	v_fmac_f32_e32 v65, v48, v48
	v_mul_f32_e32 v68, v61, v61
	v_mul_f32_e32 v69, v53, v53
	v_fmac_f32_e32 v66, v58, v58
	v_fmac_f32_e32 v67, v50, v50
	v_add_f32_e32 v62, v62, v63
	v_add_f32_e32 v63, v64, v65
	v_fmac_f32_e32 v68, v60, v60
	v_fmac_f32_e32 v69, v52, v52
	v_add_f32_e32 v64, v66, v67
	v_add_f32_e32 v62, v62, v63
	v_add_f32_e32 v65, v68, v69
	v_add_f32_e32 v62, v62, v64
	v_add_f32_e32 v62, v62, v65
	ds_bpermute_b32 v63, v14, v62
	s_waitcnt lgkmcnt(0)
	v_add_f32_e32 v62, v62, v63
	ds_bpermute_b32 v63, v15, v62
	s_waitcnt lgkmcnt(0)
	v_add_f32_e32 v62, v62, v63
	ds_bpermute_b32 v63, v16, v62
	s_waitcnt lgkmcnt(0)
	v_add_f32_e32 v62, v62, v63
	ds_bpermute_b32 v63, v17, v62
	s_waitcnt lgkmcnt(0)
	v_add_f32_e32 v62, v62, v63
	ds_bpermute_b32 v63, v18, v62
	s_waitcnt lgkmcnt(0)
	v_add_f32_e32 v62, v62, v63
	ds_bpermute_b32 v63, v19, v62
	s_waitcnt lgkmcnt(0)
	v_add_f32_e32 v62, v62, v63
	v_fmamk_f32 v62, v62, 0x3a800000, v20
	v_mul_f32_e32 v63, 0x4f800000, v62
	v_cmp_gt_f32_e32 vcc, s3, v62
	s_nop 1
	v_cndmask_b32_e32 v62, v62, v63, vcc
	v_sqrt_f32_e32 v63, v62
	s_nop 0
	v_add_u32_e32 v64, -1, v63
	v_add_u32_e32 v65, 1, v63
	v_fma_f32 v66, -v64, v63, v62
	v_fma_f32 v67, -v65, v63, v62
	v_cmp_ge_f32_e64 s[0:1], 0, v66
	s_nop 1
	v_cndmask_b32_e64 v63, v63, v64, s[0:1]
	v_cmp_lt_f32_e64 s[0:1], 0, v67
	s_nop 1
	v_cndmask_b32_e64 v63, v63, v65, s[0:1]
	v_mul_f32_e32 v64, 0x37800000, v63
	v_cndmask_b32_e32 v63, v63, v64, vcc
	v_cmp_class_f32_e32 vcc, v62, v21
	s_nop 1
	v_cndmask_b32_e32 v62, v63, v62, vcc
	v_div_scale_f32 v63, s[0:1], v62, v62, 1.0
	v_rcp_f32_e32 v65, v63
	v_div_scale_f32 v64, vcc, 1.0, v62, 1.0
	v_fma_f32 v66, -v63, v65, 1.0
	v_fmac_f32_e32 v65, v66, v65
	v_mul_f32_e32 v66, v64, v65
	v_fma_f32 v67, -v63, v66, v64
	v_fmac_f32_e32 v66, v67, v65
	v_fma_f32 v63, -v63, v66, v64
	v_div_fmas_f32 v63, v63, v65, v66
	v_div_fixup_f32 v62, v63, v62, 1.0
	v_mul_f32_e32 v62, 0.5, v62
	v_pk_mul_f32 v[54:55], v[62:63], v[54:55] op_sel_hi:[0,1]
	v_pk_mul_f32 v[46:47], v[62:63], v[46:47] op_sel_hi:[0,1]
	v_pk_mul_f32 v[56:57], v[62:63], v[56:57] op_sel_hi:[0,1]
	v_pk_mul_f32 v[48:49], v[62:63], v[48:49] op_sel_hi:[0,1]
	v_pk_mul_f32 v[58:59], v[62:63], v[58:59] op_sel_hi:[0,1]
	v_pk_mul_f32 v[50:51], v[62:63], v[50:51] op_sel_hi:[0,1]
	v_pk_mul_f32 v[60:61], v[62:63], v[60:61] op_sel_hi:[0,1]
	v_pk_mul_f32 v[52:53], v[62:63], v[52:53] op_sel_hi:[0,1]
	v_pk_fma_f32 v[24:25], v[32:33], v[46:47], v[24:25]
	v_pk_fma_f32 v[22:23], v[30:31], v[54:55], v[22:23]
	v_pk_fma_f32 v[28:29], v[36:37], v[48:49], v[28:29]
	v_pk_fma_f32 v[26:27], v[34:35], v[56:57], v[26:27]
	v_pk_fma_f32 v[6:7], v[40:41], v[50:51], v[6:7]
	v_pk_fma_f32 v[4:5], v[38:39], v[58:59], v[4:5]
	v_pk_fma_f32 v[2:3], v[44:45], v[52:53], v[2:3]
	v_pk_fma_f32 v[0:1], v[42:43], v[60:61], v[0:1]
	global_store_dwordx4 v[70:71], v[22:25], off offset:-2048
	global_store_dwordx4 v[70:71], v[26:29], off offset:-1024
	global_store_dwordx4 v[70:71], v[4:7], off
	global_store_dwordx4 v[70:71], v[0:3], off offset:1024
	s_branch .LBB0_733
.Lp11_tailB:
	s_waitcnt vmcnt(0)
	v_lshlrev_b32_e32 v154, 16, v146
	v_and_b32_e32 v155, 0xffff0000, v146
	v_lshlrev_b32_e32 v146, 16, v147
	v_and_b32_e32 v147, 0xffff0000, v147
	v_lshlrev_b32_e32 v156, 16, v148
	v_and_b32_e32 v157, 0xffff0000, v148
	v_lshlrev_b32_e32 v148, 16, v149
	v_and_b32_e32 v149, 0xffff0000, v149
	v_lshlrev_b32_e32 v158, 16, v150
	v_and_b32_e32 v159, 0xffff0000, v150
	v_lshlrev_b32_e32 v150, 16, v151
	v_and_b32_e32 v151, 0xffff0000, v151
	v_mul_f32_e32 v162, v155, v155
	v_mul_f32_e32 v163, v147, v147
	v_mul_f32_e32 v164, v157, v157
	v_mul_f32_e32 v165, v149, v149
	v_lshlrev_b32_e32 v160, 16, v152
	v_and_b32_e32 v161, 0xffff0000, v152
	v_lshlrev_b32_e32 v152, 16, v153
	v_and_b32_e32 v153, 0xffff0000, v153
	v_mul_f32_e32 v166, v159, v159
	v_mul_f32_e32 v167, v151, v151
	v_fmac_f32_e32 v162, v154, v154
	v_fmac_f32_e32 v163, v146, v146
	v_fmac_f32_e32 v164, v156, v156
	v_fmac_f32_e32 v165, v148, v148
	v_mul_f32_e32 v168, v161, v161
	v_mul_f32_e32 v169, v153, v153
	v_fmac_f32_e32 v166, v158, v158
	v_fmac_f32_e32 v167, v150, v150
	v_add_f32_e32 v162, v162, v163
	v_add_f32_e32 v163, v164, v165
	v_fmac_f32_e32 v168, v160, v160
	v_fmac_f32_e32 v169, v152, v152
	v_add_f32_e32 v164, v166, v167
	v_add_f32_e32 v162, v162, v163
	v_add_f32_e32 v165, v168, v169
	v_add_f32_e32 v162, v162, v164
	v_add_f32_e32 v162, v162, v165
	ds_bpermute_b32 v163, v14, v162
	s_waitcnt lgkmcnt(0)
	v_add_f32_e32 v162, v162, v163
	ds_bpermute_b32 v163, v15, v162
	s_waitcnt lgkmcnt(0)
	v_add_f32_e32 v162, v162, v163
	ds_bpermute_b32 v163, v16, v162
	s_waitcnt lgkmcnt(0)
	v_add_f32_e32 v162, v162, v163
	ds_bpermute_b32 v163, v17, v162
	s_waitcnt lgkmcnt(0)
	v_add_f32_e32 v162, v162, v163
	ds_bpermute_b32 v163, v18, v162
	s_waitcnt lgkmcnt(0)
	v_add_f32_e32 v162, v162, v163
	ds_bpermute_b32 v163, v19, v162
	s_waitcnt lgkmcnt(0)
	v_add_f32_e32 v162, v162, v163
	v_fmamk_f32 v162, v162, 0x3a800000, v20
	v_mul_f32_e32 v163, 0x4f800000, v162
	v_cmp_gt_f32_e32 vcc, s3, v162
	s_nop 1
	v_cndmask_b32_e32 v162, v162, v163, vcc
	v_sqrt_f32_e32 v163, v162
	s_nop 0
	v_add_u32_e32 v164, -1, v163
	v_add_u32_e32 v165, 1, v163
	v_fma_f32 v166, -v164, v163, v162
	v_fma_f32 v167, -v165, v163, v162
	v_cmp_ge_f32_e64 s[0:1], 0, v166
	s_nop 1
	v_cndmask_b32_e64 v163, v163, v164, s[0:1]
	v_cmp_lt_f32_e64 s[0:1], 0, v167
	s_nop 1
	v_cndmask_b32_e64 v163, v163, v165, s[0:1]
	v_mul_f32_e32 v164, 0x37800000, v163
	v_cndmask_b32_e32 v163, v163, v164, vcc
	v_cmp_class_f32_e32 vcc, v162, v21
	s_nop 1
	v_cndmask_b32_e32 v162, v163, v162, vcc
	v_div_scale_f32 v163, s[0:1], v162, v162, 1.0
	v_rcp_f32_e32 v165, v163
	v_div_scale_f32 v164, vcc, 1.0, v162, 1.0
	v_fma_f32 v166, -v163, v165, 1.0
	v_fmac_f32_e32 v165, v166, v165
	v_mul_f32_e32 v166, v164, v165
	v_fma_f32 v167, -v163, v166, v164
	v_fmac_f32_e32 v166, v167, v165
	v_fma_f32 v163, -v163, v166, v164
	v_div_fmas_f32 v163, v163, v165, v166
	v_div_fixup_f32 v162, v163, v162, 1.0
	v_mul_f32_e32 v162, 0.5, v162
	v_pk_mul_f32 v[154:155], v[162:163], v[154:155] op_sel_hi:[0,1]
	v_pk_mul_f32 v[146:147], v[162:163], v[146:147] op_sel_hi:[0,1]
	v_pk_mul_f32 v[156:157], v[162:163], v[156:157] op_sel_hi:[0,1]
	v_pk_mul_f32 v[148:149], v[162:163], v[148:149] op_sel_hi:[0,1]
	v_pk_mul_f32 v[158:159], v[162:163], v[158:159] op_sel_hi:[0,1]
	v_pk_mul_f32 v[150:151], v[162:163], v[150:151] op_sel_hi:[0,1]
	v_pk_mul_f32 v[160:161], v[162:163], v[160:161] op_sel_hi:[0,1]
	v_pk_mul_f32 v[152:153], v[162:163], v[152:153] op_sel_hi:[0,1]
	v_pk_fma_f32 v[124:125], v[32:33], v[146:147], v[124:125]
	v_pk_fma_f32 v[122:123], v[30:31], v[154:155], v[122:123]
	v_pk_fma_f32 v[128:129], v[36:37], v[148:149], v[128:129]
	v_pk_fma_f32 v[126:127], v[34:35], v[156:157], v[126:127]
	v_pk_fma_f32 v[106:107], v[40:41], v[150:151], v[106:107]
	v_pk_fma_f32 v[104:105], v[38:39], v[158:159], v[104:105]
	v_pk_fma_f32 v[102:103], v[44:45], v[152:153], v[102:103]
	v_pk_fma_f32 v[100:101], v[42:43], v[160:161], v[100:101]
	global_store_dwordx4 v[170:171], v[122:125], off offset:-2048
	global_store_dwordx4 v[170:171], v[126:129], off offset:-1024
	global_store_dwordx4 v[170:171], v[104:107], off
	global_store_dwordx4 v[170:171], v[100:103], off offset:1024
